# prompt-path Toeplitz loop in the same in-place-reload pipelined form as the sample stream
# speedup vs baseline: 1.0236x; 1.0004x over previous
.LBB0_472:
	s_and_b64 vcc, exec, s[48:49]
	s_cbranch_vccz .LBB0_475
	v_mov_b32_e32 v2, 0
	v_mov_b32_e32 v3, v2
	v_mov_b32_e32 v4, v2
	v_mov_b32_e32 v5, v2
	v_mov_b32_e32 v6, v2
	v_mov_b32_e32 v7, v2
	v_mov_b32_e32 v8, v2
	v_mov_b32_e32 v9, v2
	v_mov_b32_e32 v10, v2
	v_mov_b32_e32 v11, v2
	v_mov_b32_e32 v12, v2
	v_mov_b32_e32 v13, v2
	v_mov_b32_e32 v14, v2
	v_mov_b32_e32 v15, v2
	v_mov_b32_e32 v16, v2
	v_mov_b32_e32 v17, v2
	v_mov_b32_e32 v18, v2
	v_mov_b32_e32 v19, v2
	v_mov_b32_e32 v20, v2
	v_mov_b32_e32 v21, v2
	v_mov_b32_e32 v22, v2
	v_mov_b32_e32 v23, v2
	v_mov_b32_e32 v24, v2
	v_mov_b32_e32 v25, v2
	v_mov_b32_e32 v26, v2
	v_mov_b32_e32 v27, v2
	v_mov_b32_e32 v28, v2
	v_mov_b32_e32 v29, v2
	v_mov_b32_e32 v30, v2
	v_mov_b32_e32 v31, v2
	v_mov_b32_e32 v32, v2
	v_mov_b32_e32 v33, v2
	v_mov_b32_e32 v34, v2
	v_mov_b32_e32 v35, v2
	v_mov_b32_e32 v36, v2
	v_mov_b32_e32 v37, v2
	v_mov_b32_e32 v38, v2
	v_mov_b32_e32 v39, v2
	v_mov_b32_e32 v40, v2
	v_mov_b32_e32 v41, v2
	v_mov_b32_e32 v42, v2
	v_mov_b32_e32 v43, v2
	v_mov_b32_e32 v44, v2
	v_mov_b32_e32 v45, v2
	v_mov_b32_e32 v46, v2
	v_mov_b32_e32 v47, v2
	v_mov_b32_e32 v48, v2
	v_mov_b32_e32 v49, v2
	v_mov_b32_e32 v50, v2
	v_mov_b32_e32 v51, v2
	v_mov_b32_e32 v52, v2
	v_mov_b32_e32 v53, v2
	v_mov_b32_e32 v54, v2
	v_mov_b32_e32 v55, v2
	v_mov_b32_e32 v56, v2
	v_mov_b32_e32 v57, v2
	v_mov_b32_e32 v58, v2
	v_mov_b32_e32 v59, v2
	v_mov_b32_e32 v60, v2
	v_mov_b32_e32 v61, v2
	v_mov_b32_e32 v62, v2
	v_mov_b32_e32 v63, v2
	v_mov_b32_e32 v64, v2
	v_mov_b32_e32 v65, v2
	v_lshlrev_b32_e32 v206, 1, v184
	v_and_b32_e32 v206, -4, v206
	v_add_u32_e32 v206, 0x1c0, v206
	v_add_u32_e32 v206, v117, v206
	v_add_u32_e32 v209, 7, v180
	ds_read2_b32 v[194:195], v206 offset1:1
	ds_read2_b32 v[196:197], v206 offset0:2 offset1:3
	ds_read_b32 v198, v206 offset:16
	ds_read2_b32 v[200:201], v206 offset0:8 offset1:9
	ds_read2_b32 v[202:203], v206 offset0:10 offset1:11
	ds_read_b32 v204, v206 offset:48
	v_lshrrev_b32_e32 v210, 2, v209
	v_lshl_add_u32 v189, v209, 6, v182
	v_bitop3_b32 v211, v210, v113, 3 bitop3:0x6c
	v_bitop3_b32 v188, v210, v155, 3 bitop3:0x6c
	v_lshl_add_u32 v199, v211, 4, v189
	v_lshl_add_u32 v205, v188, 4, v189
	ds_read_b128 v[66:69], v199
	ds_read_b128 v[70:73], v205
	v_add_u32_e32 v207, 60, v209
	v_lshrrev_b32_e32 v210, 2, v207
	v_lshl_add_u32 v189, v207, 6, v182
	v_bitop3_b32 v211, v210, v113, 3 bitop3:0x6c
	v_bitop3_b32 v188, v210, v155, 3 bitop3:0x6c
	v_lshl_add_u32 v199, v211, 4, v189
	v_lshl_add_u32 v205, v188, 4, v189
	ds_read_b128 v[74:77], v199
	ds_read_b128 v[78:81], v205
	v_add_u32_e32 v207, 120, v209
	v_lshrrev_b32_e32 v210, 2, v207
	v_lshl_add_u32 v189, v207, 6, v182
	v_bitop3_b32 v211, v210, v113, 3 bitop3:0x6c
	v_bitop3_b32 v188, v210, v155, 3 bitop3:0x6c
	v_lshl_add_u32 v199, v211, 4, v189
	v_lshl_add_u32 v205, v188, 4, v189
	ds_read_b128 v[82:85], v199
	ds_read_b128 v[86:89], v205
	v_add_u32_e32 v207, 180, v209
	v_lshrrev_b32_e32 v210, 2, v207
	v_lshl_add_u32 v189, v207, 6, v182
	v_bitop3_b32 v211, v210, v113, 3 bitop3:0x6c
	v_bitop3_b32 v188, v210, v155, 3 bitop3:0x6c
	v_lshl_add_u32 v199, v211, 4, v189
	v_lshl_add_u32 v205, v188, 4, v189
	ds_read_b128 v[90:93], v199
	ds_read_b128 v[94:97], v205
	v_add_u32_e32 v209, -1, v209
	s_mov_b32 s42, -7
.Ltoep_prompt:
	s_waitcnt lgkmcnt(8)
	v_alignbyte_b32 v98, v195, v194, v185
	v_alignbyte_b32 v99, v196, v195, v185
	v_alignbyte_b32 v100, v197, v196, v185
	v_alignbyte_b32 v101, v198, v197, v185
	v_alignbyte_b32 v102, v201, v200, v185
	v_alignbyte_b32 v103, v202, v201, v185
	v_alignbyte_b32 v104, v203, v202, v185
	v_alignbyte_b32 v105, v204, v203, v185
	v_add_u32_e32 v206, -64, v206
	ds_read2_b32 v[194:195], v206 offset1:1
	ds_read2_b32 v[196:197], v206 offset0:2 offset1:3
	ds_read_b32 v198, v206 offset:16
	ds_read2_b32 v[200:201], v206 offset0:8 offset1:9
	ds_read2_b32 v[202:203], v206 offset0:10 offset1:11
	ds_read_b32 v204, v206 offset:48
	v_lshrrev_b32_e32 v210, 2, v209
	v_lshl_add_u32 v189, v209, 6, v182
	v_bitop3_b32 v211, v210, v113, 3 bitop3:0x6c
	v_bitop3_b32 v188, v210, v155, 3 bitop3:0x6c
	v_lshl_add_u32 v199, v211, 4, v189
	v_lshl_add_u32 v205, v188, 4, v189
	s_waitcnt lgkmcnt(13)
	v_mfma_f32_32x32x16_bf16 v[2:17], v[98:101], v[66:69], v[2:17]
	ds_read_b128 v[66:69], v199
	s_waitcnt lgkmcnt(13)
	v_mfma_f32_32x32x16_bf16 v[2:17], v[102:105], v[70:73], v[2:17]
	ds_read_b128 v[70:73], v205
	v_add_u32_e32 v207, 60, v209
	v_lshrrev_b32_e32 v210, 2, v207
	v_lshl_add_u32 v189, v207, 6, v182
	v_bitop3_b32 v211, v210, v113, 3 bitop3:0x6c
	v_bitop3_b32 v188, v210, v155, 3 bitop3:0x6c
	v_lshl_add_u32 v199, v211, 4, v189
	v_lshl_add_u32 v205, v188, 4, v189
	s_waitcnt lgkmcnt(13)
	v_mfma_f32_32x32x16_bf16 v[18:33], v[98:101], v[74:77], v[18:33]
	ds_read_b128 v[74:77], v199
	s_waitcnt lgkmcnt(13)
	v_mfma_f32_32x32x16_bf16 v[18:33], v[102:105], v[78:81], v[18:33]
	ds_read_b128 v[78:81], v205
	v_add_u32_e32 v207, 120, v209
	v_lshrrev_b32_e32 v210, 2, v207
	v_lshl_add_u32 v189, v207, 6, v182
	v_bitop3_b32 v211, v210, v113, 3 bitop3:0x6c
	v_bitop3_b32 v188, v210, v155, 3 bitop3:0x6c
	v_lshl_add_u32 v199, v211, 4, v189
	v_lshl_add_u32 v205, v188, 4, v189
	s_waitcnt lgkmcnt(13)
	v_mfma_f32_32x32x16_bf16 v[34:49], v[98:101], v[82:85], v[34:49]
	ds_read_b128 v[82:85], v199
	s_waitcnt lgkmcnt(13)
	v_mfma_f32_32x32x16_bf16 v[34:49], v[102:105], v[86:89], v[34:49]
	ds_read_b128 v[86:89], v205
	v_add_u32_e32 v207, 180, v209
	v_lshrrev_b32_e32 v210, 2, v207
	v_lshl_add_u32 v189, v207, 6, v182
	v_bitop3_b32 v211, v210, v113, 3 bitop3:0x6c
	v_bitop3_b32 v188, v210, v155, 3 bitop3:0x6c
	v_lshl_add_u32 v199, v211, 4, v189
	v_lshl_add_u32 v205, v188, 4, v189
	s_waitcnt lgkmcnt(13)
	v_mfma_f32_32x32x16_bf16 v[50:65], v[98:101], v[90:93], v[50:65]
	ds_read_b128 v[90:93], v199
	s_waitcnt lgkmcnt(13)
	v_mfma_f32_32x32x16_bf16 v[50:65], v[102:105], v[94:97], v[50:65]
	ds_read_b128 v[94:97], v205
	v_add_u32_e32 v209, -1, v209
	s_add_i32 s42, s42, 1
	s_cmp_lt_i32 s42, 7
	s_cbranch_scc1 .Ltoep_prompt
	s_waitcnt lgkmcnt(0)
	v_alignbyte_b32 v98, v195, v194, v185
	v_alignbyte_b32 v99, v196, v195, v185
	v_alignbyte_b32 v100, v197, v196, v185
	v_alignbyte_b32 v101, v198, v197, v185
	v_alignbyte_b32 v102, v201, v200, v185
	v_alignbyte_b32 v103, v202, v201, v185
	v_alignbyte_b32 v104, v203, v202, v185
	v_alignbyte_b32 v105, v204, v203, v185
	s_nop 1
	v_mfma_f32_32x32x16_bf16 v[2:17], v[98:101], v[66:69], v[2:17]
	v_mfma_f32_32x32x16_bf16 v[2:17], v[102:105], v[70:73], v[2:17]
	v_mfma_f32_32x32x16_bf16 v[18:33], v[98:101], v[74:77], v[18:33]
	v_mfma_f32_32x32x16_bf16 v[18:33], v[102:105], v[78:81], v[18:33]
	v_mfma_f32_32x32x16_bf16 v[34:49], v[98:101], v[82:85], v[34:49]
	v_mfma_f32_32x32x16_bf16 v[34:49], v[102:105], v[86:89], v[34:49]
	v_mfma_f32_32x32x16_bf16 v[50:65], v[98:101], v[90:93], v[50:65]
	v_mfma_f32_32x32x16_bf16 v[50:65], v[102:105], v[94:97], v[50:65]
